# k4: LRU / ctx-query short items split off the MLA queues into their own atomic queues that blocks on the GQA XCDs drain first (overlap with attention instead of a tail); hw_sum steps via DPP row_ror
# baseline (speedup 1.0000x reference)
; DI int xcc_id() { return (int)(__builtin_amdgcn_s_getreg((3 << 11) | 20) & 7u); }
; __global__ void __launch_bounds__(256, 2) mega(P p) {
;     ...
;         const int g0 = xcc_id();
;         for (int gi = 0; gi < 8; ++gi) {
;         const int g = (g0 + gi) & 7;
;         unsigned* gctr = ctrs + 128 + ph2 * 8 + g;
;         const int tot = (g < 4) ? 84 : 24 + 128;
;         for (int iq = next_item(gctr, &s_item); iq < tot; iq = next_item(gctr, &s_item)) {
.LBB0_53:
	s_add_i32 s47, s47, 1
	s_add_i32 s48, s48, 1
	v_readlane_b32 s62, v254, 58
	s_cmp_eq_u32 s47, 12
	v_readlane_b32 s49, v255, 12
	v_readlane_b32 s63, v254, 59
	s_cbranch_scc1 .LBB0_171
.LBB0_54:
	s_cmp_gt_u32 s86, 3
	s_cselect_b32 s0, 4, 0
	s_sub_i32 s0, s47, s0
	s_cmp_gt_u32 s0, 7
	s_cselect_b32 s1, 32, 0
	s_add_i32 s20, s0, s86
	s_and_b32 s20, s20, 7
	s_and_b32 s0, s20, 3
	s_cmp_lg_u32 s1, 0
	s_cselect_b32 s20, s0, s20
	s_mov_b32 s48, s20
	s_lshl_b32 s21, s20, 2
	s_add_u32 s2, s87, s21
	s_addc_u32 s3, s88, 0
	s_add_u32 s2, s2, s1
	s_addc_u32 s3, s3, 0
	s_barrier
	s_and_saveexec_b64 s[0:1], s[96:97]
	s_cbranch_execz .LBB0_58
	s_mov_b64 s[16:17], exec
	v_mbcnt_lo_u32_b32 v0, s16, 0
	v_mbcnt_hi_u32_b32 v0, s17, v0
	v_cmp_eq_u32_e32 vcc, 0, v0
	s_and_saveexec_b64 s[10:11], vcc
	s_cbranch_execz .LBB0_57
	s_bcnt1_i32_b64 s16, s[16:17]
	v_mov_b32_e32 v1, s16
	global_atomic_add v1, v97, v1, s[2:3] offset:512 sc0

; __global__ void __launch_bounds__(256, 2) mega(P p) {
;     ...
;         for (int iq = next_item(gctr, &s_item); iq < tot; iq = next_item(gctr, &s_item)) {
;           const int i = (g < 4) ? (iq < 64 ? 20 + iq : (iq < 80 ? iq - 64 : 16 + (iq - 80)))
;                                 : (iq < 8 ? iq : (iq < 136 ? 24 + (iq - 8) : 8 + (iq - 136)));
.LBB0_58:
	s_or_b64 exec, exec, s[0:1]
	s_waitcnt lgkmcnt(0)
	s_barrier
	ds_read_b32 v0, v205
	s_cmp_gt_u32 s86, 3
	s_cselect_b32 s0, 4, 0
	s_sub_i32 s0, s47, s0
	s_cmp_gt_u32 s0, 7
	s_cselect_b32 s1, 64, 0
	s_cselect_b32 s0, 0x54, 64
	s_cmp_gt_u32 s20, 3
	s_cselect_b64 s[22:23], -1, 0
	s_cmp_lt_u32 s20, 4
	s_cselect_b32 s49, s0, 0x98
	s_waitcnt lgkmcnt(0)
	v_add_u32_e32 v0, s1, v0
	v_cmp_le_i32_e32 vcc, s49, v0
	v_readfirstlane_b32 s16, v0
	s_cbranch_vccnz .LBB0_53
	s_and_b32 s0, s48, 7
	s_lshl_b32 s46, s0, 2
	s_mul_i32 s24, s0, 0x210000
	s_mul_i32 s1, s0, 0x318000
	s_lshl_b32 s45, s0, 7
	s_add_i32 s0, s0, -4
	s_mul_i32 s11, s20, 0x210000
	s_lshr_b32 s0, s0, 1
	s_add_i32 s76, s20, -4
	s_add_i32 s18, s11, 0xff7c0000
	v_readlane_b32 s19, v252, 60
	s_mul_hi_u32 s10, s76, 0x210000
	s_add_u32 s26, s19, s18
	v_readlane_b32 s18, v252, 61
	s_addc_u32 s27, s18, s10
	s_lshr_b32 s10, s76, 1
	s_mul_hi_u32 s18, s10, 0x210000
	s_mul_i32 s10, s10, 0x210000
	v_readlane_b32 s19, v252, 62
	s_add_u32 s28, s19, s10
	v_readlane_b32 s19, v252, 63
	s_addc_u32 s29, s19, s18
	v_readlane_b32 s30, v253, 0
	v_readlane_b32 s31, v253, 1
	s_add_u32 s80, s30, s10
	s_addc_u32 s81, s31, s18
	s_lshl_b32 s36, s20, 7
	s_lshl_b32 s10, s20, 3
	s_add_i32 s89, s36, 0xfffffdc0
	s_sub_i32 s62, s10, 32
	s_mul_i32 s10, s20, 0x318000
	v_readlane_b32 s18, v253, 14
	s_add_u32 s38, s18, s10
	v_readlane_b32 s18, v253, 15
	s_addc_u32 s39, s18, 0
	v_readlane_b32 s18, v253, 16
	s_add_u32 s18, s18, s10
	v_readlane_b32 s10, v253, 17
	s_addc_u32 s19, s10, 0
	v_readlane_b32 s30, v253, 18
	v_readlane_b32 s31, v253, 19
	s_add_u32 s10, s30, s11
	s_addc_u32 s11, s31, 0
	s_lshl_b32 s37, s20, 8
	v_readlane_b32 s30, v253, 20
	s_add_u32 s40, s30, s37
	v_readlane_b32 s30, v253, 21
	s_addc_u32 s41, s30, 0
	s_or_b32 s63, s36, 0x600
	s_lshr_b32 s30, s63, 6
	s_lshl_b32 s36, s20, 1
	v_writelane_b32 v255, s30, 19
	s_add_i32 s30, s36, 25
	s_lshl_b32 s90, s20, 4
	s_mul_hi_u32 s17, s0, 0x210000
	s_mul_i32 s0, s0, 0x210000
	v_writelane_b32 v255, s30, 27
	s_add_i32 s21, s21, -16
	s_add_i32 s90, s90, 64
	v_writelane_b32 v255, s21, 29
	s_add_u32 s20, s94, s0
	v_writelane_b32 v255, s20, 31
	s_addc_u32 s20, s95, s17
	v_writelane_b32 v255, s20, 33
	v_readlane_b32 s20, v254, 52
	v_readlane_b32 s21, v254, 53
	s_add_u32 s30, s20, s0
	s_addc_u32 s31, s21, s17
	s_addk_i32 s45, 0xfdc0
	s_add_u32 s42, s1, 0x183840c0
	s_mov_b32 s25, s75
	s_addc_u32 s43, 0, 0
	s_add_i32 s46, s46, -16
	s_branch .LBB0_62

; __global__ void __launch_bounds__(256, 2) mega(P p) {
;     ...
;         for (int iq = next_item(gctr, &s_item); iq < tot; iq = next_item(gctr, &s_item)) {
.LBB0_61:
	s_or_b64 exec, exec, s[0:1]
	s_waitcnt lgkmcnt(0)
	s_barrier
	ds_read_b32 v0, v205
	s_cmp_gt_u32 s86, 3
	s_cselect_b32 s0, 4, 0
	s_sub_i32 s0, s47, s0
	s_cmp_gt_u32 s0, 7
	s_cselect_b32 s1, 64, 0
	s_waitcnt lgkmcnt(0)
	v_add_u32_e32 v0, s1, v0
	v_cmp_le_i32_e32 vcc, s49, v0
	v_readfirstlane_b32 s16, v0
	s_cbranch_vccnz .LBB0_53
